# opt10
# speedup vs baseline: 1.0533x; 1.0029x over previous
; __device__ void dsa_item(const Ctx& cx, CParamsPtr pp, int item, char* shm) {
;     ...
;       uint32_t prefix = 0;
; #pragma unroll 1
;     ...
;         const uint32_t cand = prefix | (1u << bit);
;         int cnt = 0;
; #pragma unroll
;         for (int i = 0; i < 32; ++i) cnt += __builtin_popcountll(__ballot(u[i] >= cand));
;         if (cnt >= 256) prefix = cand;
;       }
;       int cgt = 0;
; #pragma unroll
;       for (int i = 0; i < 32; ++i) cgt += __builtin_popcountll(__ballot(u[i] > prefix));
;       const int need = 256 - cgt;
;       const unsigned long long lt = (lane == 0) ? 0ull : (~0ull >> (64 - lane));
;       int base = 0, eqc = 0;
; #pragma unroll
;       for (int i = 0; i < 32; ++i) {
;         const bool eq = (u[i] == prefix);
;         const unsigned long long em = __ballot(eq);
;         const int eqb = eqc + __builtin_popcountll(em & lt);
;         const bool sel = (u[i] > prefix) || (eq && eqb < need);
;         const unsigned long long sm = __ballot(sel);
;         if (sel) idxl[base + __builtin_popcountll(sm & lt)] = lane + 64 * i;
.LBB0_116:
	s_lshl_b32 s0, 1, s4
	s_or_b32 s5, s0, s80
	v_cmp_le_u32_e32 vcc, s5, v148
	s_bcnt1_i32_b64 s0, vcc
	v_cmp_le_u32_e32 vcc, s5, v147
	s_bcnt1_i32_b64 s1, vcc
	v_cmp_le_u32_e32 vcc, s5, v146
	s_add_i32 s0, s1, s0
	s_bcnt1_i32_b64 s1, vcc
	v_cmp_le_u32_e32 vcc, s5, v4
	s_add_i32 s0, s0, s1
	s_bcnt1_i32_b64 s1, vcc
	v_cmp_le_u32_e32 vcc, s5, v145
	s_add_i32 s0, s0, s1
	s_bcnt1_i32_b64 s1, vcc
	v_cmp_le_u32_e32 vcc, s5, v143
	s_add_i32 s0, s0, s1
	s_bcnt1_i32_b64 s1, vcc
	v_cmp_le_u32_e32 vcc, s5, v144
	s_add_i32 s0, s0, s1
	s_bcnt1_i32_b64 s1, vcc
	v_cmp_le_u32_e32 vcc, s5, v141
	s_add_i32 s0, s0, s1
	s_bcnt1_i32_b64 s1, vcc
	v_cmp_le_u32_e32 vcc, s5, v142
	s_add_i32 s0, s0, s1
	s_bcnt1_i32_b64 s1, vcc
	v_cmp_le_u32_e32 vcc, s5, v35
	s_add_i32 s0, s0, s1
	s_bcnt1_i32_b64 s1, vcc
	v_cmp_le_u32_e32 vcc, s5, v37
	s_add_i32 s0, s0, s1
	s_bcnt1_i32_b64 s1, vcc
	v_cmp_le_u32_e32 vcc, s5, v33
	s_add_i32 s0, s0, s1
	s_bcnt1_i32_b64 s1, vcc
	v_cmp_le_u32_e32 vcc, s5, v34
	s_add_i32 s0, s0, s1
	s_bcnt1_i32_b64 s1, vcc
	v_cmp_le_u32_e32 vcc, s5, v29
	s_add_i32 s0, s0, s1
	s_bcnt1_i32_b64 s1, vcc
	v_cmp_le_u32_e32 vcc, s5, v31
	s_add_i32 s0, s0, s1
	s_bcnt1_i32_b64 s1, vcc
	v_cmp_le_u32_e32 vcc, s5, v19
	s_add_i32 s0, s0, s1
	s_bcnt1_i32_b64 s1, vcc
	v_cmp_le_u32_e32 vcc, s5, v27
	s_add_i32 s0, s0, s1
	s_bcnt1_i32_b64 s1, vcc
	v_cmp_le_u32_e32 vcc, s5, v16
	s_add_i32 s0, s0, s1
	s_bcnt1_i32_b64 s1, vcc
	v_cmp_le_u32_e32 vcc, s5, v18
	s_add_i32 s0, s0, s1
	s_bcnt1_i32_b64 s1, vcc
	v_cmp_le_u32_e32 vcc, s5, v14
	s_add_i32 s0, s0, s1
	s_bcnt1_i32_b64 s1, vcc
	v_cmp_le_u32_e32 vcc, s5, v17
	s_add_i32 s0, s0, s1
	s_bcnt1_i32_b64 s1, vcc
	v_cmp_le_u32_e32 vcc, s5, v12
	s_add_i32 s0, s0, s1
	s_bcnt1_i32_b64 s1, vcc
	v_cmp_le_u32_e32 vcc, s5, v15
	s_add_i32 s0, s0, s1
	s_bcnt1_i32_b64 s1, vcc
	v_cmp_le_u32_e32 vcc, s5, v10
	s_add_i32 s0, s0, s1
	s_bcnt1_i32_b64 s1, vcc
	v_cmp_le_u32_e32 vcc, s5, v13
	s_add_i32 s0, s0, s1
	s_bcnt1_i32_b64 s1, vcc
	v_cmp_le_u32_e32 vcc, s5, v8
	s_add_i32 s0, s0, s1
	s_bcnt1_i32_b64 s1, vcc
	v_cmp_le_u32_e32 vcc, s5, v11
	s_add_i32 s0, s0, s1
	s_bcnt1_i32_b64 s1, vcc
	v_cmp_le_u32_e32 vcc, s5, v6
	s_add_i32 s0, s0, s1
	s_bcnt1_i32_b64 s1, vcc
	v_cmp_le_u32_e32 vcc, s5, v9
	s_add_i32 s0, s0, s1
	s_bcnt1_i32_b64 s1, vcc
	v_cmp_le_u32_e32 vcc, s5, v5
	s_add_i32 s0, s0, s1
	s_bcnt1_i32_b64 s1, vcc
	v_cmp_le_u32_e32 vcc, s5, v7
	s_add_i32 s6, s0, s1
	s_bcnt1_i32_b64 s0, vcc
	v_cmp_le_u32_e32 vcc, s5, v1
	s_add_i32 s6, s6, s0
	s_bcnt1_i32_b64 s0, vcc
	s_add_i32 s6, s6, s0
	s_cmpk_gt_u32 s6, 0xff
	s_cselect_b32 s80, s5, s80
	s_cmpk_eq_u32 s6, 0x100
	s_cbranch_scc1 .Lmy_topk_done
	s_add_i32 s4, s4, -1
	s_cmp_eq_u32 s4, -1
	s_cbranch_scc0 .LBB0_116
.Lmy_topk_done:
	v_cmp_lt_u32_e64 s[64:65], s80, v148
	v_cmp_lt_u32_e64 s[62:63], s80, v147
	s_bcnt1_i32_b64 s4, s[64:65]
	s_bcnt1_i32_b64 s5, s[62:63]
	v_cmp_lt_u32_e64 s[60:61], s80, v146
	s_bcnt1_i32_b64 s33, s[60:61]
	v_cmp_lt_u32_e64 s[58:59], s80, v4
	s_add_i32 s4, s4, s5
	s_bcnt1_i32_b64 s66, s[58:59]
	v_cmp_lt_u32_e64 s[56:57], s80, v145
	s_add_i32 s33, s4, s33
	s_bcnt1_i32_b64 s67, s[56:57]
	v_cmp_lt_u32_e64 s[54:55], s80, v143
	s_add_i32 s33, s33, s66
	s_bcnt1_i32_b64 s68, s[54:55]
	v_cmp_lt_u32_e64 s[52:53], s80, v144
	s_add_i32 s33, s33, s67
	s_bcnt1_i32_b64 s70, s[52:53]
	v_cmp_lt_u32_e64 s[50:51], s80, v141
	s_add_i32 s33, s33, s68
	s_bcnt1_i32_b64 s71, s[50:51]
	v_cmp_lt_u32_e64 s[48:49], s80, v142
	s_add_i32 s33, s33, s70
	s_bcnt1_i32_b64 s92, s[48:49]
	v_cmp_lt_u32_e64 s[46:47], s80, v35
	s_add_i32 s33, s33, s71
	s_bcnt1_i32_b64 s93, s[46:47]
	v_cmp_lt_u32_e64 s[44:45], s80, v37
	s_add_i32 s33, s33, s92
	s_bcnt1_i32_b64 s86, s[44:45]
	v_cmp_lt_u32_e64 s[42:43], s80, v33
	s_add_i32 s33, s33, s93
	s_bcnt1_i32_b64 s75, s[42:43]
	v_cmp_lt_u32_e64 s[40:41], s80, v34
	s_add_i32 s33, s33, s86
	s_bcnt1_i32_b64 s88, s[40:41]
	v_cmp_lt_u32_e64 s[38:39], s80, v29
	s_add_i32 s33, s33, s75
	s_bcnt1_i32_b64 s89, s[38:39]
	v_cmp_lt_u32_e64 s[36:37], s80, v31
	s_add_i32 s33, s33, s88
	s_bcnt1_i32_b64 s94, s[36:37]
	v_cmp_lt_u32_e64 s[34:35], s80, v19
	s_add_i32 s33, s33, s89
	s_bcnt1_i32_b64 s95, s[34:35]
	v_cmp_lt_u32_e64 s[30:31], s80, v27
	s_add_i32 s33, s33, s94
	s_bcnt1_i32_b64 s90, s[30:31]
	v_cmp_lt_u32_e64 s[28:29], s80, v16
	s_add_i32 s33, s33, s95
	s_bcnt1_i32_b64 s74, s[28:29]
	v_cmp_lt_u32_e64 s[26:27], s80, v18
	s_add_i32 s33, s33, s90
	s_bcnt1_i32_b64 s77, s[26:27]
	v_cmp_lt_u32_e64 s[24:25], s80, v14
	s_add_i32 s33, s33, s74
	s_bcnt1_i32_b64 s81, s[24:25]
	v_cmp_lt_u32_e64 s[22:23], s80, v17
	s_add_i32 s33, s33, s77
	s_bcnt1_i32_b64 s91, s[22:23]
	v_cmp_lt_u32_e64 s[20:21], s80, v12
	s_add_i32 s33, s33, s81
	s_bcnt1_i32_b64 s1, s[20:21]
	v_cmp_lt_u32_e64 s[18:19], s80, v15
	s_add_i32 s33, s33, s91
	s_bcnt1_i32_b64 s78, s[18:19]
	v_cmp_lt_u32_e64 s[16:17], s80, v10
	s_add_i32 s1, s33, s1
	s_bcnt1_i32_b64 s79, s[16:17]
	v_cmp_lt_u32_e64 s[14:15], s80, v13
	s_add_i32 s1, s1, s78
	s_bcnt1_i32_b64 s76, s[14:15]
	v_cmp_lt_u32_e64 s[12:13], s80, v8
	s_add_i32 s1, s1, s79
	s_bcnt1_i32_b64 s87, s[12:13]
	v_cmp_lt_u32_e64 s[10:11], s80, v11
	s_add_i32 s1, s1, s76
	s_bcnt1_i32_b64 s0, s[10:11]
	v_cmp_lt_u32_e64 s[8:9], s80, v6
	s_add_i32 s1, s1, s87
	s_bcnt1_i32_b64 s72, s[8:9]
	v_cmp_lt_u32_e64 s[6:7], s80, v9
	s_add_i32 s0, s1, s0
	s_bcnt1_i32_b64 s73, s[6:7]
	v_cmp_lt_u32_e64 s[4:5], s80, v5
	s_add_i32 s0, s0, s72
	s_bcnt1_i32_b64 s66, s[4:5]
	v_cmp_lt_u32_e64 s[68:69], s80, v7
	s_add_i32 s0, s0, s73
	s_bcnt1_i32_b64 s67, s[68:69]
	s_add_i32 s0, s0, s66
	v_cmp_lt_u32_e32 vcc, s80, v1
	s_add_i32 s0, s0, s67
	v_cmp_eq_u32_e64 s[66:67], s80, v148
	s_bcnt1_i32_b64 s70, vcc
	s_add_i32 s0, s0, s70
	v_and_b32_e32 v149, s66, v24
	v_and_b32_e32 v148, s67, v25
	v_bcnt_u32_b32 v149, v149, 0
	s_sub_i32 s33, 0x100, s0
	v_bcnt_u32_b32 v148, v148, v149
	v_cmp_gt_i32_e64 s[70:71], s33, v148
	s_and_b64 s[70:71], s[66:67], s[70:71]
	s_or_b64 s[92:93], s[64:65], s[70:71]
	v_cndmask_b32_e64 v148, 0, 1, s[92:93]
	v_cmp_ne_u32_e64 s[64:65], 0, v148
	s_and_saveexec_b64 s[70:71], s[92:93]
	s_cbranch_execz .LBB0_119
	v_and_b32_e32 v149, s64, v24
	v_and_b32_e32 v148, s65, v25
	v_bcnt_u32_b32 v149, v149, 0
	v_bcnt_u32_b32 v148, v148, v149
	v_lshl_add_u32 v148, v148, 2, v38
	ds_write_b32 v148, v20
